# grid barrier variant: arrival atomic issued before the LDS read, no s_sleep in the poll loop
# speedup vs baseline: 1.0079x; 1.0029x over previous
.LBB0_233:
	s_waitcnt vmcnt(0)
	s_waitcnt vmcnt(0)
	s_barrier
	s_and_saveexec_b64 s[0:1], s[10:11]
	s_cbranch_execz .LBB0_285
	s_lshl_b32 s2, s19, 8
	s_add_u32 s2, s42, s2
	s_addc_u32 s3, s43, 0
	v_mov_b32_e32 v1, 0x1000
	v_mov_b32_e32 v2, 1
	v_mov_b32_e32 v0, 0x23fc0
	s_waitcnt vmcnt(0) expcnt(0) lgkmcnt(0)
	global_atomic_add v1, v1, v2, s[2:3] offset:1024 sc0
	ds_read_b64 v[4:5], v0
	s_waitcnt lgkmcnt(0)
	v_readfirstlane_b32 s8, v4
	v_readfirstlane_b32 s9, v5
	s_mul_i32 s72, s8, 2
	s_mul_i32 s73, s9, 2
	s_waitcnt vmcnt(0)
	v_readfirstlane_b32 s74, v1
	s_add_i32 s74, s74, 1
	s_cmp_lg_u32 s74, s72
	s_cbranch_scc1 .Lgb1_poll
	buffer_wbl2 sc1
	s_waitcnt vmcnt(0)
	v_mov_b32_e32 v1, 0x3323000
	global_atomic_add v1, v2, s[44:45] offset:1024

.Lgb1_spin:
	global_load_dword v4, v1, s[44:45] offset:1024 sc1
	s_waitcnt vmcnt(0)
	v_readfirstlane_b32 s78, v4
	s_cmp_ge_u32 s78, s73
	s_cbranch_scc1 .Lgb1_rel
	s_add_i32 s77, s77, 1
	s_cmp_lt_u32 s77, 0x40000
	s_cbranch_scc1 .Lgb1_spin

.LBB0_317:
	s_or_b64 exec, exec, s[0:1]
	s_waitcnt vmcnt(0)
	s_waitcnt lgkmcnt(0)
	s_barrier
	s_and_saveexec_b64 s[0:1], s[10:11]
	s_cbranch_execz .LBB0_369
	s_lshl_b32 s2, s19, 8
	s_add_u32 s2, s42, s2
	s_addc_u32 s3, s43, 0
	v_mov_b32_e32 v1, 0x1000
	v_mov_b32_e32 v2, 1
	v_mov_b32_e32 v0, 0x23fc0
	s_waitcnt vmcnt(0) expcnt(0) lgkmcnt(0)
	global_atomic_add v1, v1, v2, s[2:3] offset:1024 sc0
	ds_read_b64 v[4:5], v0
	s_waitcnt lgkmcnt(0)
	v_readfirstlane_b32 s8, v4
	v_readfirstlane_b32 s9, v5
	s_mul_i32 s72, s8, 3
	s_mul_i32 s73, s9, 3
	s_waitcnt vmcnt(0)
	v_readfirstlane_b32 s74, v1
	s_add_i32 s74, s74, 1
	s_cmp_lg_u32 s74, s72
	s_cbranch_scc1 .Lgb2_poll
	buffer_wbl2 sc1
	s_waitcnt vmcnt(0)
	v_mov_b32_e32 v1, 0x3323000
	global_atomic_add v1, v2, s[44:45] offset:1024

.LBB0_593:
	s_waitcnt vmcnt(0)
	s_waitcnt vmcnt(0)
	s_barrier
	s_and_saveexec_b64 s[0:1], s[10:11]
	s_cbranch_execz .LBB0_645
	s_lshl_b32 s2, s19, 8
	s_add_u32 s2, s42, s2
	s_addc_u32 s3, s43, 0
	v_mov_b32_e32 v1, 0x1000
	v_mov_b32_e32 v2, 1
	v_mov_b32_e32 v0, 0x23fc0
	s_waitcnt vmcnt(0) expcnt(0) lgkmcnt(0)
	global_atomic_add v1, v1, v2, s[2:3] offset:1024 sc0
	ds_read_b64 v[4:5], v0
	s_waitcnt lgkmcnt(0)
	v_readfirstlane_b32 s8, v4
	v_readfirstlane_b32 s9, v5
	s_mul_i32 s72, s8, 4
	s_mul_i32 s73, s9, 4
	s_waitcnt vmcnt(0)
	v_readfirstlane_b32 s74, v1
	s_add_i32 s74, s74, 1
	s_cmp_lg_u32 s74, s72
	s_cbranch_scc1 .Lgb3_poll
	buffer_wbl2 sc1
	s_waitcnt vmcnt(0)
	v_mov_b32_e32 v1, 0x3323000
	global_atomic_add v1, v2, s[44:45] offset:1024

.LBB0_667:
	s_waitcnt vmcnt(0)
	s_waitcnt lgkmcnt(0)
	s_barrier
	s_and_saveexec_b64 s[0:1], s[10:11]
	s_cbranch_execz .LBB0_719
	s_lshl_b32 s2, s19, 8
	s_add_u32 s2, s42, s2
	s_addc_u32 s3, s43, 0
	v_mov_b32_e32 v1, 0x1000
	v_mov_b32_e32 v2, 1
	v_mov_b32_e32 v0, 0x23fc0
	s_waitcnt vmcnt(0) expcnt(0) lgkmcnt(0)
	global_atomic_add v1, v1, v2, s[2:3] offset:1024 sc0
	ds_read_b64 v[4:5], v0
	s_waitcnt lgkmcnt(0)
	v_readfirstlane_b32 s8, v4
	v_readfirstlane_b32 s9, v5
	s_mul_i32 s72, s8, 5
	s_mul_i32 s73, s9, 5
	s_waitcnt vmcnt(0)
	v_readfirstlane_b32 s74, v1
	s_add_i32 s74, s74, 1
	s_cmp_lg_u32 s74, s72
	s_cbranch_scc1 .Lgb4_poll
	buffer_wbl2 sc1
	s_waitcnt vmcnt(0)
	v_mov_b32_e32 v1, 0x3323000
	global_atomic_add v1, v2, s[44:45] offset:1024

.LBB0_975:
	s_setprio 0
	s_waitcnt vmcnt(0)
	s_barrier
	s_and_saveexec_b64 s[0:1], s[10:11]
	s_cbranch_execz .LBB0_1027
	s_lshl_b32 s2, s19, 8
	s_add_u32 s2, s42, s2
	s_addc_u32 s3, s43, 0
	v_mov_b32_e32 v1, 0x1000
	v_mov_b32_e32 v2, 1
	v_mov_b32_e32 v0, 0x23fc0
	s_waitcnt vmcnt(0) expcnt(0) lgkmcnt(0)
	global_atomic_add v1, v1, v2, s[2:3] offset:1024 sc0
	ds_read_b64 v[4:5], v0
	s_waitcnt lgkmcnt(0)
	v_readfirstlane_b32 s8, v4
	v_readfirstlane_b32 s9, v5
	s_mul_i32 s72, s8, 6
	s_mul_i32 s73, s9, 6
	s_waitcnt vmcnt(0)
	v_readfirstlane_b32 s74, v1
	s_add_i32 s74, s74, 1
	s_cmp_lg_u32 s74, s72
	s_cbranch_scc1 .Lgb5_poll
	buffer_wbl2 sc1
	s_waitcnt vmcnt(0)
	v_mov_b32_e32 v1, 0x3323000
	global_atomic_add v1, v2, s[44:45] offset:1024

.LBB0_1051:
	s_waitcnt vmcnt(0)
	s_barrier
	s_and_saveexec_b64 s[0:1], s[10:11]
	s_cbranch_execz .LBB0_1103
	s_lshl_b32 s2, s19, 8
	s_add_u32 s2, s42, s2
	s_addc_u32 s3, s43, 0
	v_mov_b32_e32 v1, 0x1000
	v_mov_b32_e32 v2, 1
	v_mov_b32_e32 v0, 0x23fc0
	s_waitcnt vmcnt(0) expcnt(0) lgkmcnt(0)
	global_atomic_add v1, v1, v2, s[2:3] offset:1024 sc0
	ds_read_b64 v[4:5], v0
	s_waitcnt lgkmcnt(0)
	v_readfirstlane_b32 s8, v4
	v_readfirstlane_b32 s9, v5
	s_mul_i32 s72, s8, 7
	s_mul_i32 s73, s9, 7
	s_waitcnt vmcnt(0)
	v_readfirstlane_b32 s74, v1
	s_add_i32 s74, s74, 1
	s_cmp_lg_u32 s74, s72
	s_cbranch_scc1 .Lgb6_poll
	buffer_wbl2 sc1
	s_waitcnt vmcnt(0)
	v_mov_b32_e32 v1, 0x3323000
	global_atomic_add v1, v2, s[44:45] offset:1024

.LBB0_1127:
	s_waitcnt vmcnt(0)
	s_barrier
	s_and_saveexec_b64 s[0:1], s[10:11]
	s_cbranch_execz .LBB0_1179
	s_lshl_b32 s2, s19, 8
	s_add_u32 s2, s42, s2
	s_addc_u32 s3, s43, 0
	v_mov_b32_e32 v1, 0x1000
	v_mov_b32_e32 v2, 1
	v_mov_b32_e32 v0, 0x23fc0
	s_waitcnt vmcnt(0) expcnt(0) lgkmcnt(0)
	global_atomic_add v1, v1, v2, s[2:3] offset:1024 sc0
	ds_read_b64 v[4:5], v0
	s_waitcnt lgkmcnt(0)
	v_readfirstlane_b32 s8, v4
	v_readfirstlane_b32 s9, v5
	s_mul_i32 s72, s8, 8
	s_mul_i32 s73, s9, 8
	s_waitcnt vmcnt(0)
	v_readfirstlane_b32 s74, v1
	s_add_i32 s74, s74, 1
	s_cmp_lg_u32 s74, s72
	s_cbranch_scc1 .Lgb7_poll
	buffer_wbl2 sc1
	s_waitcnt vmcnt(0)
	v_mov_b32_e32 v1, 0x3323000
	global_atomic_add v1, v2, s[44:45] offset:1024

.LBB0_1237:
	s_waitcnt vmcnt(0)
	s_barrier
	s_and_saveexec_b64 s[0:1], s[10:11]
	s_cbranch_execz .LBB0_1289
	s_lshl_b32 s2, s19, 8
	s_add_u32 s2, s42, s2
	s_addc_u32 s3, s43, 0
	v_mov_b32_e32 v1, 0x1000
	v_mov_b32_e32 v2, 1
	v_mov_b32_e32 v0, 0x23fc0
	s_waitcnt vmcnt(0) expcnt(0) lgkmcnt(0)
	global_atomic_add v1, v1, v2, s[2:3] offset:1024 sc0
	ds_read_b64 v[4:5], v0
	s_waitcnt lgkmcnt(0)
	v_readfirstlane_b32 s8, v4
	v_readfirstlane_b32 s9, v5
	s_mul_i32 s72, s8, 9
	s_mul_i32 s73, s9, 9
	s_waitcnt vmcnt(0)
	v_readfirstlane_b32 s74, v1
	s_add_i32 s74, s74, 1
	s_cmp_lg_u32 s74, s72
	s_cbranch_scc1 .Lgb8_poll
	buffer_wbl2 sc1
	s_waitcnt vmcnt(0)
	v_mov_b32_e32 v1, 0x3323000
	global_atomic_add v1, v2, s[44:45] offset:1024

.LBB0_1305:
	s_waitcnt vmcnt(0)
	s_barrier
	s_and_saveexec_b64 s[0:1], s[10:11]
	s_cbranch_execz .LBB0_1357
	s_lshl_b32 s2, s19, 8
	s_add_u32 s2, s42, s2
	s_addc_u32 s3, s43, 0
	v_mov_b32_e32 v1, 0x1000
	v_mov_b32_e32 v2, 1
	v_mov_b32_e32 v0, 0x23fc0
	s_waitcnt vmcnt(0) expcnt(0) lgkmcnt(0)
	global_atomic_add v1, v1, v2, s[2:3] offset:1024 sc0
	ds_read_b64 v[4:5], v0
	s_waitcnt lgkmcnt(0)
	v_readfirstlane_b32 s8, v4
	v_readfirstlane_b32 s9, v5
	s_mul_i32 s72, s8, 10
	s_mul_i32 s73, s9, 10
	s_waitcnt vmcnt(0)
	v_readfirstlane_b32 s74, v1
	s_add_i32 s74, s74, 1
	s_cmp_lg_u32 s74, s72
	s_cbranch_scc1 .Lgb9_poll
	buffer_wbl2 sc1
	s_waitcnt vmcnt(0)
	v_mov_b32_e32 v1, 0x3323000
	global_atomic_add v1, v2, s[44:45] offset:1024

.LBB0_1367:
	s_waitcnt vmcnt(0)
	s_barrier
	s_and_saveexec_b64 s[0:1], s[10:11]
	s_cbranch_execz .LBB0_1419
	s_lshl_b32 s2, s19, 8
	s_add_u32 s2, s42, s2
	s_addc_u32 s3, s43, 0
	v_mov_b32_e32 v1, 0x1000
	v_mov_b32_e32 v2, 1
	v_mov_b32_e32 v0, 0x23fc0
	s_waitcnt vmcnt(0) expcnt(0) lgkmcnt(0)
	global_atomic_add v1, v1, v2, s[2:3] offset:1024 sc0
	ds_read_b64 v[4:5], v0
	s_waitcnt lgkmcnt(0)
	v_readfirstlane_b32 s8, v4
	v_readfirstlane_b32 s9, v5
	s_mul_i32 s72, s8, 11
	s_mul_i32 s73, s9, 11
	s_waitcnt vmcnt(0)
	v_readfirstlane_b32 s74, v1
	s_add_i32 s74, s74, 1
	s_cmp_lg_u32 s74, s72
	s_cbranch_scc1 .Lgb10_poll
	buffer_wbl2 sc1
	s_waitcnt vmcnt(0)
	v_mov_b32_e32 v1, 0x3323000
	global_atomic_add v1, v2, s[44:45] offset:1024

.LBB0_1787:
	s_setprio 0
	s_waitcnt vmcnt(0)
	s_barrier
	s_and_saveexec_b64 s[0:1], s[10:11]
	s_cbranch_execz .LBB0_1839
	s_lshl_b32 s2, s19, 8
	s_add_u32 s2, s42, s2
	s_addc_u32 s3, s43, 0
	v_mov_b32_e32 v1, 0x1000
	v_mov_b32_e32 v2, 1
	v_mov_b32_e32 v0, 0x23fc0
	s_waitcnt vmcnt(0) expcnt(0) lgkmcnt(0)
	global_atomic_add v1, v1, v2, s[2:3] offset:1024 sc0
	ds_read_b64 v[4:5], v0
	s_waitcnt lgkmcnt(0)
	v_readfirstlane_b32 s8, v4
	v_readfirstlane_b32 s9, v5
	s_mul_i32 s72, s8, 12
	s_mul_i32 s73, s9, 12
	s_waitcnt vmcnt(0)
	v_readfirstlane_b32 s74, v1
	s_add_i32 s74, s74, 1
	s_cmp_lg_u32 s74, s72
	s_cbranch_scc1 .Lgb11_poll
	buffer_wbl2 sc1
	s_waitcnt vmcnt(0)
	v_mov_b32_e32 v1, 0x3323000
	global_atomic_add v1, v2, s[44:45] offset:1024

.LBB0_1867:
	s_waitcnt vmcnt(0)
	s_barrier
	s_and_saveexec_b64 s[0:1], s[10:11]
	s_cbranch_execz .LBB0_1919
	s_lshl_b32 s2, s19, 8
	s_add_u32 s2, s42, s2
	s_addc_u32 s3, s43, 0
	v_mov_b32_e32 v1, 0x1000
	v_mov_b32_e32 v2, 1
	v_mov_b32_e32 v0, 0x23fc0
	s_waitcnt vmcnt(0) expcnt(0) lgkmcnt(0)
	global_atomic_add v1, v1, v2, s[2:3] offset:1024 sc0
	ds_read_b64 v[4:5], v0
	s_waitcnt lgkmcnt(0)
	v_readfirstlane_b32 s8, v4
	v_readfirstlane_b32 s9, v5
	s_mul_i32 s72, s8, 13
	s_mul_i32 s73, s9, 13
	s_waitcnt vmcnt(0)
	v_readfirstlane_b32 s74, v1
	s_add_i32 s74, s74, 1
	s_cmp_lg_u32 s74, s72
	s_cbranch_scc1 .Lgb12_poll
	buffer_wbl2 sc1
	s_waitcnt vmcnt(0)
	v_mov_b32_e32 v1, 0x3323000
	global_atomic_add v1, v2, s[44:45] offset:1024

.LBB0_1943:
	s_waitcnt vmcnt(0)
	s_barrier
	s_and_saveexec_b64 s[0:1], s[10:11]
	s_cbranch_execz .LBB0_1995
	s_lshl_b32 s2, s19, 8
	s_add_u32 s2, s42, s2
	s_addc_u32 s3, s43, 0
	v_mov_b32_e32 v1, 0x1000
	v_mov_b32_e32 v2, 1
	v_mov_b32_e32 v0, 0x23fc0
	s_waitcnt vmcnt(0) expcnt(0) lgkmcnt(0)
	global_atomic_add v1, v1, v2, s[2:3] offset:1024 sc0
	ds_read_b64 v[4:5], v0
	s_waitcnt lgkmcnt(0)
	v_readfirstlane_b32 s8, v4
	v_readfirstlane_b32 s9, v5
	s_mul_i32 s72, s8, 14
	s_mul_i32 s73, s9, 14
	s_waitcnt vmcnt(0)
	v_readfirstlane_b32 s74, v1
	s_add_i32 s74, s74, 1
	s_cmp_lg_u32 s74, s72
	s_cbranch_scc1 .Lgb13_poll
	buffer_wbl2 sc1
	s_waitcnt vmcnt(0)
	v_mov_b32_e32 v1, 0x3323000
	global_atomic_add v1, v2, s[44:45] offset:1024
